# combo5 + next-row prefetch in the layer-1 renorm/modulate row loop (its 4 row loads were issued one at a time with vmcnt(0) each)
# speedup vs baseline: 1.0096x; 1.0017x over previous
; template <int MODE, bool SRC32>
; __device__ __forceinline__ void phase_mod(const float* x32, _Float16* xh, float* out32, bf16* h, const float* gprev, const float* gain, const float* shiftv, const float* scalev, int wave, int lane) {
;     const int blk = (int)blockIdx.x, b = blk >> 5, r0 = blk * 128 + wave * 16;
;     f32x4 A[8], Sh[8], G3[8];
; #pragma unroll
;     for (int k = 0; k < 8; ++k) {
;         const int d = 512 * (k >> 1) + 8 * lane + 4 * (k & 1);
;         if (MODE != 2) { const f32x4 g = *(const f32x4*)(gain + d), sc = *(const f32x4*)(scalev + (size_t)b * NMOD + d); A[k] = g * (sc + 1.0f); Sh[k] = *(const f32x4*)(shiftv + (size_t)b * NMOD + d); }
;         if (MODE != 0) G3[k] = *(const f32x4*)(gprev + d);
;     }
;     for (int i = 0; i < 16; ++i) {
;         const size_t ro = (size_t)(r0 + i) * D + 8 * lane;
;         f32x4 v[8]; float ss = 0.f;
; #pragma unroll
;         for (int j = 0; j < 4; ++j) {
;             if (SRC32) { v[2 * j] = *(const f32x4*)(x32 + ro + 512 * j); v[2 * j + 1] = *(const f32x4*)(x32 + ro + 512 * j + 4); }
;             else h8_to_f(*(const h16x8*)(xh + ro + 512 * j), v[2 * j], v[2 * j + 1]);
;         }
.LBB0_98:
	v_writelane_b32 v255, s20, 2
	s_andn2_b64 vcc, exec, s[0:1]
	s_xor_b64 s[30:31], s[4:5], -1
	v_writelane_b32 v255, s21, 3
	s_cbranch_vccnz .LBB0_151
	v_readlane_b32 s0, v254, 44
	v_readlane_b32 s1, v254, 45
	s_lshl_b32 s12, s6, 4
	s_lshl_b64 s[0:1], s[0:1], 2
	s_add_u32 s6, s55, s0
	s_addc_u32 s7, s60, s1
	v_lshlrev_b32_e32 v168, 3, v68
	s_add_u32 s8, s6, 0x2000
	s_addc_u32 s9, s7, 0
	s_waitcnt vmcnt(0)
	v_lshlrev_b64 v[0:1], 2, v[168:169]
	v_lshl_add_u64 v[78:79], s[8:9], 0, v[0:1]
	global_load_dwordx4 v[4:7], v[78:79], off
	v_lshl_add_u64 v[76:77], s[20:21], 0, v[0:1]
	global_load_dwordx4 v[8:11], v[76:77], off
	v_lshl_add_u64 v[70:71], s[6:7], 0, v[0:1]
	global_load_dwordx4 v[0:3], v[70:71], off
	s_mov_b64 s[0:1], -1
	v_or_b32_e32 v74, 0x400, v168
	v_or_b32_e32 v72, 0x600, v168
	s_and_b64 vcc, exec, s[30:31]
	s_waitcnt vmcnt(2)
	v_pk_add_f32 v[6:7], v[6:7], 1.0 op_sel_hi:[1,0]
	v_pk_add_f32 v[4:5], v[4:5], 1.0 op_sel_hi:[1,0]
	s_waitcnt vmcnt(1)
	v_pk_mul_f32 v[64:65], v[10:11], v[6:7]
	v_pk_mul_f32 v[66:67], v[8:9], v[4:5]
	s_cbranch_vccz .LBB0_103
	v_readlane_b32 s0, v253, 5
	v_readlane_b32 s1, v253, 6
	v_mov_b32_e32 v75, v169
	v_lshlrev_b64 v[40:41], 2, v[74:75]
	v_lshl_add_u64 v[8:9], v[168:169], 2, s[0:1]
	global_load_dwordx4 v[4:7], v[8:9], off offset:16
	s_nop 0
	global_load_dwordx4 v[8:11], v[8:9], off
	s_nop 0
	global_load_dwordx4 v[12:15], v[76:77], off offset:16
	global_load_dwordx4 v[16:19], v[78:79], off offset:16
	v_or_b32_e32 v168, 0x200, v168
	v_lshl_add_u64 v[28:29], v[168:169], 2, s[0:1]
	v_mov_b32_e32 v73, v169
	v_lshlrev_b64 v[56:57], 2, v[72:73]
	v_lshl_add_u64 v[44:45], s[0:1], 0, v[40:41]
	v_lshl_add_u64 v[60:61], s[0:1], 0, v[56:57]
	v_cmp_lt_i32_e32 vcc, v222, v216
	v_readlane_b32 s0, v253, 7
	s_add_i32 s0, s12, s0
	v_cndmask_b32_e32 v69, v215, v222, vcc
	v_cmp_lt_i32_e32 vcc, v221, v216
	v_lshlrev_b32_e32 v73, 2, v69
	s_ashr_i32 s1, s0, 31
	v_cndmask_b32_e32 v69, v215, v221, vcc
	v_cmp_lt_i32_e32 vcc, v220, v216
	v_lshlrev_b32_e32 v75, 2, v69
	s_lshl_b64 s[0:1], s[0:1], 12
	v_cndmask_b32_e32 v69, v215, v220, vcc
	v_cmp_lt_i32_e32 vcc, v219, v216
	s_add_u32 s0, s42, s0
	s_addc_u32 s1, s43, s1
	s_mov_b64 s[10:11], 0
	s_waitcnt vmcnt(0)
	v_pk_add_f32 v[18:19], v[18:19], 1.0 op_sel_hi:[1,0]
	v_pk_add_f32 v[16:17], v[16:17], 1.0 op_sel_hi:[1,0]
	v_pk_mul_f32 v[80:81], v[14:15], v[18:19]
	v_pk_mul_f32 v[82:83], v[12:13], v[16:17]
	global_load_dwordx4 v[12:15], v[70:71], off offset:16
	global_load_dwordx4 v[32:35], v[76:77], off offset:2064
	global_load_dwordx4 v[16:19], v[76:77], off offset:2048
	global_load_dwordx4 v[36:39], v[78:79], off offset:2064
	global_load_dwordx4 v[20:23], v[78:79], off offset:2048
	s_waitcnt vmcnt(1)
	v_pk_add_f32 v[36:37], v[36:37], 1.0 op_sel_hi:[1,0]
	s_waitcnt vmcnt(0)
	v_pk_add_f32 v[22:23], v[22:23], 1.0 op_sel_hi:[1,0]
	v_pk_add_f32 v[20:21], v[20:21], 1.0 op_sel_hi:[1,0]
	v_pk_add_f32 v[38:39], v[38:39], 1.0 op_sel_hi:[1,0]
	v_pk_mul_f32 v[90:91], v[32:33], v[36:37]
	v_lshl_add_u64 v[32:33], s[20:21], 0, v[40:41]
	v_lshl_add_u64 v[36:37], s[8:9], 0, v[40:41]
	v_pk_mul_f32 v[84:85], v[18:19], v[22:23]
	v_pk_mul_f32 v[86:87], v[16:17], v[20:21]
	global_load_dwordx4 v[16:19], v[70:71], off offset:2064
	global_load_dwordx4 v[20:23], v[70:71], off offset:2048
	global_load_dwordx4 v[24:27], v[28:29], off offset:16
	s_nop 0
	global_load_dwordx4 v[28:31], v[28:29], off
	v_pk_mul_f32 v[88:89], v[34:35], v[38:39]
	global_load_dwordx4 v[48:51], v[32:33], off offset:16
	s_nop 0
	global_load_dwordx4 v[32:35], v[32:33], off
	s_nop 0
	global_load_dwordx4 v[52:55], v[36:37], off offset:16
	s_nop 0
	global_load_dwordx4 v[36:39], v[36:37], off
	s_waitcnt vmcnt(1)
	v_pk_add_f32 v[52:53], v[52:53], 1.0 op_sel_hi:[1,0]
	s_waitcnt vmcnt(0)
	v_pk_add_f32 v[36:37], v[36:37], 1.0 op_sel_hi:[1,0]
	v_pk_add_f32 v[38:39], v[38:39], 1.0 op_sel_hi:[1,0]
	v_pk_mul_f32 v[94:95], v[32:33], v[36:37]
	v_lshl_add_u64 v[36:37], s[6:7], 0, v[40:41]
	v_pk_add_f32 v[54:55], v[54:55], 1.0 op_sel_hi:[1,0]
	v_pk_mul_f32 v[98:99], v[48:49], v[52:53]
	v_lshl_add_u64 v[48:49], s[20:21], 0, v[56:57]
	v_lshl_add_u64 v[52:53], s[8:9], 0, v[56:57]
	v_pk_mul_f32 v[92:93], v[34:35], v[38:39]
	global_load_dwordx4 v[32:35], v[36:37], off offset:16
	s_nop 0
	global_load_dwordx4 v[36:39], v[36:37], off
	s_nop 0
	global_load_dwordx4 v[40:43], v[44:45], off offset:16
	s_nop 0
	global_load_dwordx4 v[44:47], v[44:45], off
	v_pk_mul_f32 v[96:97], v[50:51], v[54:55]
	global_load_dwordx4 v[106:109], v[48:49], off offset:16
	s_nop 0
	global_load_dwordx4 v[48:51], v[48:49], off
	s_nop 0
	global_load_dwordx4 v[110:113], v[52:53], off offset:16
	s_nop 0
	global_load_dwordx4 v[52:55], v[52:53], off
	s_waitcnt vmcnt(1)
	v_pk_add_f32 v[104:105], v[112:113], 1.0 op_sel_hi:[1,0]
	s_waitcnt vmcnt(0)
	v_pk_add_f32 v[52:53], v[52:53], 1.0 op_sel_hi:[1,0]
	v_pk_add_f32 v[54:55], v[54:55], 1.0 op_sel_hi:[1,0]
	v_pk_mul_f32 v[102:103], v[48:49], v[52:53]
	v_lshl_add_u64 v[52:53], s[6:7], 0, v[56:57]
	v_pk_mul_f32 v[100:101], v[50:51], v[54:55]
	global_load_dwordx4 v[48:51], v[52:53], off offset:16
	s_nop 0
	global_load_dwordx4 v[52:55], v[52:53], off
	s_nop 0
	global_load_dwordx4 v[56:59], v[60:61], off offset:16
	s_nop 0
	global_load_dwordx4 v[60:63], v[60:61], off
	v_lshlrev_b32_e32 v112, 2, v69
	v_cndmask_b32_e32 v69, v215, v219, vcc
	v_cmp_lt_i32_e32 vcc, v218, v216
	v_lshlrev_b32_e32 v113, 2, v69
	v_pk_add_f32 v[110:111], v[110:111], 1.0 op_sel_hi:[1,0]
	v_cndmask_b32_e32 v69, v215, v218, vcc
	v_cmp_lt_i32_e32 vcc, v217, v216
	v_lshlrev_b32_e32 v114, 2, v69
	v_pk_mul_f32 v[104:105], v[108:109], v[104:105]
	v_cndmask_b32_e32 v69, v215, v217, vcc
	v_lshlrev_b32_e32 v115, 2, v69
	v_mov_b32_e32 v69, v169
	v_pk_mul_f32 v[106:107], v[106:107], v[110:111]
	v_lshl_add_u64 v[108:109], v[68:69], 4, s[0:1]
	v_add_co_u32_e32 v204, vcc, 0x4ae00000, v108
	v_mov_b32_e32 v206, 0x1000
	v_mov_b32_e32 v207, 0
	v_addc_co_u32_e32 v205, vcc, 0, v109, vcc
	global_load_dwordx4 v[188:191], v[204:205], off
	global_load_dwordx4 v[192:195], v[204:205], off offset:1024
	global_load_dwordx4 v[196:199], v[204:205], off offset:2048
	global_load_dwordx4 v[200:203], v[204:205], off offset:3072
	s_waitcnt vmcnt(0)
; template <int MODE, bool SRC32>
; __device__ __forceinline__ void phase_mod(const float* x32, _Float16* xh, float* out32, bf16* h, const float* gprev, const float* gain, const float* shiftv, const float* scalev, int wave, int lane) {
;     ...
;         const size_t ro = (size_t)(r0 + i) * D + 8 * lane;
;         f32x4 v[8]; float ss = 0.f;
; #pragma unroll
;         for (int j = 0; j < 4; ++j) {
;             if (SRC32) { v[2 * j] = *(const f32x4*)(x32 + ro + 512 * j); v[2 * j + 1] = *(const f32x4*)(x32 + ro + 512 * j + 4); }
;             else h8_to_f(*(const h16x8*)(xh + ro + 512 * j), v[2 * j], v[2 * j + 1]);
;         }
; #pragma unroll
;         for (int k = 0; k < 8; ++k) ss += (v[k][0] * v[k][0] + v[k][1] * v[k][1]) + (v[k][2] * v[k][2] + v[k][3] * v[k][3]);
;         ss = wave_sum(ss);
;         float rstd = 1.0f / sqrtf(ss * (1.0f / D) + EPS);
;         if (MODE != 0) {
;             float s2 = 0.f;
; #pragma unroll
;             for (int k = 0; k < 8; ++k) { v[k] = v[k] * rstd * G3[k]; s2 += (v[k][0] * v[k][0] + v[k][1] * v[k][1]) + (v[k][2] * v[k][2] + v[k][3] * v[k][3]); }
.LBB0_101:
	v_lshl_add_u64 v[110:111], v[108:109], 0, s[10:11]
	v_add_co_u32_e32 v120, vcc, 0x4ae00000, v110
	s_add_u32 s10, s10, 0x1000
	s_nop 0
	v_addc_co_u32_e32 v121, vcc, 0, v111, vcc
	s_addc_u32 s11, s11, 0
	s_cmp_lg_u32 s10, 0x10000
	s_waitcnt vmcnt(11)
	v_cvt_f32_f16_e32 v122, v188
	v_cvt_f32_f16_sdwa v123, v188 dst_sel:DWORD dst_unused:UNUSED_PAD src0_sel:WORD_1
	v_cvt_f32_f16_e32 v124, v189
	v_cvt_f32_f16_sdwa v125, v189 dst_sel:DWORD dst_unused:UNUSED_PAD src0_sel:WORD_1
	v_cvt_f32_f16_e32 v126, v190
	v_cvt_f32_f16_sdwa v127, v190 dst_sel:DWORD dst_unused:UNUSED_PAD src0_sel:WORD_1
	v_cvt_f32_f16_e32 v128, v191
	v_cvt_f32_f16_sdwa v129, v191 dst_sel:DWORD dst_unused:UNUSED_PAD src0_sel:WORD_1
	v_mov_b32_e32 v152, v123
	v_mov_b32_e32 v153, v127
	v_mov_b32_e32 v150, v122
	v_mov_b32_e32 v151, v126
	v_pk_mul_f32 v[152:153], v[152:153], v[152:153]
	v_mov_b32_e32 v154, v125
	v_mov_b32_e32 v155, v129
	v_pk_fma_f32 v[150:151], v[150:151], v[150:151], v[152:153]
	v_mov_b32_e32 v152, v124
	v_mov_b32_e32 v153, v128
	v_pk_mul_f32 v[154:155], v[154:155], v[154:155]
	s_waitcnt vmcnt(10)
	v_cvt_f32_f16_e32 v130, v192
	v_cvt_f32_f16_sdwa v131, v192 dst_sel:DWORD dst_unused:UNUSED_PAD src0_sel:WORD_1
	v_cvt_f32_f16_e32 v132, v193
	v_cvt_f32_f16_sdwa v133, v193 dst_sel:DWORD dst_unused:UNUSED_PAD src0_sel:WORD_1
	v_cvt_f32_f16_e32 v134, v194
	v_cvt_f32_f16_sdwa v135, v194 dst_sel:DWORD dst_unused:UNUSED_PAD src0_sel:WORD_1
	v_cvt_f32_f16_e32 v136, v195
	v_cvt_f32_f16_sdwa v137, v195 dst_sel:DWORD dst_unused:UNUSED_PAD src0_sel:WORD_1
	v_pk_fma_f32 v[152:153], v[152:153], v[152:153], v[154:155]
	v_mov_b32_e32 v154, v131
	v_pk_add_f32 v[150:151], v[150:151], v[152:153]
	v_mov_b32_e32 v155, v133
	v_pk_add_f32 v[150:151], v[150:151], v[150:151] op_sel_hi:[0,1]
	v_mov_b32_e32 v152, v130
	v_mov_b32_e32 v153, v132
	v_pk_mul_f32 v[154:155], v[154:155], v[154:155]
	v_mul_f32_e32 v150, v134, v134
	v_pk_fma_f32 v[152:153], v[152:153], v[152:153], v[154:155]
	v_pk_fma_f32 v[154:155], v[134:135], v[134:135], v[150:151] op_sel_hi:[1,1,0]
	v_mul_f32_e32 v150, v136, v136
	v_pk_add_f32 v[152:153], v[152:153], v[152:153] op_sel_hi:[0,1]
	v_pk_fma_f32 v[156:157], v[136:137], v[136:137], v[150:151] op_sel_hi:[1,1,0]
	s_waitcnt vmcnt(9)
	v_cvt_f32_f16_e32 v138, v196
	v_cvt_f32_f16_sdwa v139, v196 dst_sel:DWORD dst_unused:UNUSED_PAD src0_sel:WORD_1
	v_cvt_f32_f16_e32 v140, v197
	v_cvt_f32_f16_sdwa v141, v197 dst_sel:DWORD dst_unused:UNUSED_PAD src0_sel:WORD_1
	v_cvt_f32_f16_e32 v142, v198
	v_cvt_f32_f16_sdwa v143, v198 dst_sel:DWORD dst_unused:UNUSED_PAD src0_sel:WORD_1
	v_cvt_f32_f16_e32 v144, v199
	v_cvt_f32_f16_sdwa v145, v199 dst_sel:DWORD dst_unused:UNUSED_PAD src0_sel:WORD_1
	v_pk_mul_f32 v[158:159], v[138:139], v[138:139]
	v_pk_mul_f32 v[160:161], v[140:141], v[140:141]
	v_mov_b32_e32 v154, v158
	v_mov_b32_e32 v156, v159
	v_mov_b32_e32 v150, v160
	v_mov_b32_e32 v152, v161
	v_pk_add_f32 v[154:155], v[154:155], v[156:157]
	v_pk_add_f32 v[150:151], v[150:151], v[152:153]
	v_mov_b32_e32 v152, v142
	v_pk_add_f32 v[150:151], v[154:155], v[150:151]
	v_mov_b32_e32 v154, v143
	v_pk_add_f32 v[150:151], v[150:151], v[150:151] op_sel_hi:[0,1]
	v_mov_b32_e32 v155, v145
	v_mov_b32_e32 v153, v144
	v_pk_mul_f32 v[154:155], v[154:155], v[154:155]
	s_waitcnt vmcnt(8)
	v_cvt_f32_f16_e32 v146, v200
	v_cvt_f32_f16_sdwa v147, v200 dst_sel:DWORD dst_unused:UNUSED_PAD src0_sel:WORD_1
	v_cvt_f32_f16_e32 v116, v201
	v_cvt_f32_f16_sdwa v117, v201 dst_sel:DWORD dst_unused:UNUSED_PAD src0_sel:WORD_1
	v_cvt_f32_f16_e32 v148, v202
	v_cvt_f32_f16_sdwa v149, v202 dst_sel:DWORD dst_unused:UNUSED_PAD src0_sel:WORD_1
	v_cvt_f32_f16_e32 v118, v203
	v_cvt_f32_f16_sdwa v119, v203 dst_sel:DWORD dst_unused:UNUSED_PAD src0_sel:WORD_1
	s_cbranch_scc0 .Lmodpf_a_skip
	v_lshl_add_u64 v[204:205], v[204:205], 0, v[206:207]
	global_load_dwordx4 v[188:191], v[204:205], off
	global_load_dwordx4 v[192:195], v[204:205], off offset:1024
	global_load_dwordx4 v[196:199], v[204:205], off offset:2048
	global_load_dwordx4 v[200:203], v[204:205], off offset:3072
.Lmodpf_a_skip:
	v_mul_f32_e32 v150, v146, v146
	v_pk_fma_f32 v[152:153], v[152:153], v[152:153], v[154:155]
	v_pk_fma_f32 v[154:155], v[146:147], v[146:147], v[150:151] op_sel_hi:[1,1,0]
	v_mul_f32_e32 v150, v116, v116
	v_pk_add_f32 v[152:153], v[152:153], v[152:153] op_sel_hi:[0,1]
	v_pk_fma_f32 v[156:157], v[116:117], v[116:117], v[150:151] op_sel_hi:[1,1,0]
	v_pk_mul_f32 v[158:159], v[148:149], v[148:149]
	v_pk_mul_f32 v[160:161], v[118:119], v[118:119]
	v_mov_b32_e32 v154, v158
	v_mov_b32_e32 v156, v159
	v_mov_b32_e32 v152, v160
	v_mov_b32_e32 v150, v161
	v_pk_add_f32 v[154:155], v[154:155], v[156:157]
	v_pk_add_f32 v[150:151], v[152:153], v[150:151]
	s_nop 0
	v_pk_add_f32 v[150:151], v[154:155], v[150:151]
	s_nop 0
	v_add_f32_e32 v69, v150, v151
	ds_bpermute_b32 v150, v73, v69
	s_waitcnt lgkmcnt(0)
	v_add_f32_e32 v69, v69, v150
	ds_bpermute_b32 v150, v75, v69
	s_waitcnt lgkmcnt(0)
	v_add_f32_e32 v69, v69, v150
	ds_bpermute_b32 v150, v112, v69
	s_waitcnt lgkmcnt(0)
	v_add_f32_e32 v69, v69, v150
	ds_bpermute_b32 v150, v113, v69
	s_waitcnt lgkmcnt(0)
	v_add_f32_e32 v69, v69, v150
	ds_bpermute_b32 v150, v114, v69
	s_waitcnt lgkmcnt(0)
	v_add_f32_e32 v69, v69, v150
	ds_bpermute_b32 v150, v115, v69
	s_waitcnt lgkmcnt(0)
; __device__ __forceinline__ h16x8 f_to_h8(const f32x4 a, const f32x4 b) { return (h16x8){(_Float16)a[0], (_Float16)a[1], (_Float16)a[2], (_Float16)a[3], (_Float16)b[0], (_Float16)b[1], (_Float16)b[2], (_Float16)b[3]}; }
; template <int MODE, bool SRC32>
; __device__ __forceinline__ void phase_mod(const float* x32, _Float16* xh, float* out32, bf16* h, const float* gprev, const float* gain, const float* shiftv, const float* scalev, int wave, int lane) {
;     ...
;         ss = wave_sum(ss);
;         float rstd = 1.0f / sqrtf(ss * (1.0f / D) + EPS);
;         if (MODE != 0) {
;             float s2 = 0.f;
; #pragma unroll
;             for (int k = 0; k < 8; ++k) { v[k] = v[k] * rstd * G3[k]; s2 += (v[k][0] * v[k][0] + v[k][1] * v[k][1]) + (v[k][2] * v[k][2] + v[k][3] * v[k][3]); }
; #pragma unroll
;             for (int j = 0; j < 4; ++j) {
;                 if (MODE == 1) *(h16x8*)(xh + ro + 512 * j) = f_to_h8(v[2 * j], v[2 * j + 1]);
;                 else { *(f32x4*)(out32 + ro + 512 * j) = v[2 * j]; *(f32x4*)(out32 + ro + 512 * j + 4) = v[2 * j + 1]; }
;             }
;             if (MODE == 2) continue;
;             s2 = wave_sum(s2);
	v_add_f32_e32 v69, v69, v150
	v_fmamk_f32 v69, v69, 0x3a000000, v223
	v_cmp_gt_f32_e32 vcc, s62, v69
	v_mul_f32_e32 v150, 0x4f800000, v69
	s_nop 0
	v_cndmask_b32_e32 v69, v69, v150, vcc
	v_sqrt_f32_e32 v150, v69
	s_nop 0
	v_add_u32_e32 v151, -1, v150
	v_fma_f32 v152, -v151, v150, v69
	v_cmp_ge_f32_e64 s[36:37], 0, v152
	v_add_u32_e32 v152, 1, v150
	s_nop 0
	v_cndmask_b32_e64 v151, v150, v151, s[36:37]
	v_fma_f32 v150, -v152, v150, v69
	v_cmp_lt_f32_e64 s[36:37], 0, v150
	s_nop 1
	v_cndmask_b32_e64 v150, v151, v152, s[36:37]
	v_mul_f32_e32 v151, 0x37800000, v150
	v_cndmask_b32_e32 v150, v150, v151, vcc
	v_cmp_class_f32_e32 vcc, v69, v224
	s_nop 1
	v_cndmask_b32_e32 v69, v150, v69, vcc
	v_div_scale_f32 v150, s[0:1], v69, v69, 1.0
	v_rcp_f32_e32 v151, v150
	s_nop 0
	v_fma_f32 v152, -v150, v151, 1.0
	v_fmac_f32_e32 v151, v152, v151
	v_div_scale_f32 v152, vcc, 1.0, v69, 1.0
	v_mul_f32_e32 v153, v152, v151
	v_fma_f32 v154, -v150, v153, v152
	v_fmac_f32_e32 v153, v154, v151
	v_fma_f32 v150, -v150, v153, v152
	v_div_fmas_f32 v150, v150, v151, v153
	v_div_fixup_f32 v150, v150, v69, 1.0
	v_pk_mul_f32 v[142:143], v[142:143], v[150:151] op_sel_hi:[1,0]
	v_pk_mul_f32 v[144:145], v[144:145], v[150:151] op_sel_hi:[1,0]
	v_pk_mul_f32 v[142:143], v[40:41], v[142:143]
	v_pk_mul_f32 v[144:145], v[42:43], v[144:145]
	v_pk_mul_f32 v[162:163], v[142:143], v[142:143]
	v_pk_mul_f32 v[160:161], v[144:145], v[144:145]
	v_pk_mul_f32 v[146:147], v[146:147], v[150:151] op_sel_hi:[1,0]
	v_pk_mov_b32 v[164:165], v[162:163], v[160:161] op_sel:[1,0]
	v_mov_b32_e32 v163, v161
	v_pk_mul_f32 v[116:117], v[116:117], v[150:151] op_sel_hi:[1,0]
	v_pk_mul_f32 v[146:147], v[60:61], v[146:147]
	v_pk_add_f32 v[160:161], v[164:165], v[162:163]
	v_pk_mul_f32 v[162:163], v[62:63], v[116:117]
	v_mul_f32_e32 v116, v146, v146
	v_pk_mul_f32 v[122:123], v[122:123], v[150:151] op_sel_hi:[1,0]
	v_pk_mul_f32 v[124:125], v[124:125], v[150:151] op_sel_hi:[1,0]
	v_pk_mul_f32 v[126:127], v[126:127], v[150:151] op_sel_hi:[1,0]
	v_pk_mul_f32 v[128:129], v[128:129], v[150:151] op_sel_hi:[1,0]
	v_pk_fma_f32 v[164:165], v[146:147], v[146:147], v[116:117] op_sel_hi:[1,1,0]
	v_mul_f32_e32 v116, v162, v162
	v_pk_mul_f32 v[124:125], v[10:11], v[124:125]
	v_pk_mul_f32 v[122:123], v[8:9], v[122:123]
	v_pk_mul_f32 v[128:129], v[6:7], v[128:129]
	v_pk_mul_f32 v[126:127], v[4:5], v[126:127]
	v_pk_mul_f32 v[130:131], v[130:131], v[150:151] op_sel_hi:[1,0]
	v_pk_mul_f32 v[132:133], v[132:133], v[150:151] op_sel_hi:[1,0]
	v_pk_mul_f32 v[134:135], v[134:135], v[150:151] op_sel_hi:[1,0]
	v_pk_mul_f32 v[136:137], v[136:137], v[150:151] op_sel_hi:[1,0]
	v_pk_fma_f32 v[166:167], v[162:163], v[162:163], v[116:117] op_sel_hi:[1,1,0]
	v_pk_mul_f32 v[116:117], v[148:149], v[150:151] op_sel_hi:[1,0]
	v_pk_mul_f32 v[118:119], v[118:119], v[150:151] op_sel_hi:[1,0]
	v_pk_mul_f32 v[132:133], v[30:31], v[132:133]
	v_pk_mul_f32 v[130:131], v[28:29], v[130:131]
	v_pk_mul_f32 v[136:137], v[26:27], v[136:137]
	v_pk_mul_f32 v[134:135], v[24:25], v[134:135]
	v_pk_mul_f32 v[138:139], v[138:139], v[150:151] op_sel_hi:[1,0]
	v_pk_mul_f32 v[140:141], v[140:141], v[150:151] op_sel_hi:[1,0]
	v_pk_mul_f32 v[148:149], v[58:59], v[118:119]
	v_pk_mul_f32 v[150:151], v[56:57], v[116:117]
	v_cvt_pk_f16_f32 v119, v128, v129
	v_cvt_pk_f16_f32 v118, v126, v127
	v_cvt_pk_f16_f32 v117, v124, v125
	v_cvt_pk_f16_f32 v116, v122, v123
	v_pk_mul_f32 v[140:141], v[46:47], v[140:141]
	v_pk_mul_f32 v[138:139], v[44:45], v[138:139]
	global_store_dwordx4 v[120:121], v[116:119], off
	v_pk_mul_f32 v[152:153], v[132:133], v[132:133]
	v_pk_mul_f32 v[154:155], v[130:131], v[130:131]
	v_cvt_pk_f16_f32 v119, v136, v137
	v_cvt_pk_f16_f32 v118, v134, v135
	v_cvt_pk_f16_f32 v117, v132, v133
	v_cvt_pk_f16_f32 v116, v130, v131
	global_store_dwordx4 v[120:121], v[116:119], off offset:1024
	v_pk_mov_b32 v[156:157], v[154:155], v[152:153] op_sel:[1,0]
	v_mov_b32_e32 v155, v153
	v_cvt_pk_f16_f32 v119, v144, v145
	v_cvt_pk_f16_f32 v118, v142, v143
	v_cvt_pk_f16_f32 v117, v140, v141
	v_cvt_pk_f16_f32 v116, v138, v139
	global_store_dwordx4 v[120:121], v[116:119], off offset:2048
	v_pk_add_f32 v[152:153], v[156:157], v[154:155]
	v_mul_f32_e32 v158, v141, v141
	v_cvt_pk_f16_f32 v119, v148, v149
	v_cvt_pk_f16_f32 v118, v150, v151
	v_cvt_pk_f16_f32 v117, v162, v163
	v_cvt_pk_f16_f32 v116, v146, v147
	global_store_dwordx4 v[120:121], v[116:119], off offset:3072
	v_mov_b32_e32 v120, v125
	v_mov_b32_e32 v121, v129
	v_mov_b32_e32 v116, v123
	v_mov_b32_e32 v117, v127
	v_mov_b32_e32 v118, v124
	v_mov_b32_e32 v119, v128
	v_pk_mul_f32 v[120:121], v[120:121], v[120:121]
	v_pk_add_f32 v[152:153], v[152:153], v[152:153] op_sel_hi:[0,1]
	v_pk_mul_f32 v[116:117], v[116:117], v[116:117]
	v_pk_fma_f32 v[118:119], v[118:119], v[118:119], v[120:121]
	v_mov_b32_e32 v120, v122
	v_mov_b32_e32 v121, v126
	v_mul_f32_e32 v152, v134, v134
	v_pk_fma_f32 v[116:117], v[120:121], v[120:121], v[116:117]
	v_pk_fma_f32 v[154:155], v[134:135], v[134:135], v[152:153] op_sel_hi:[1,1,0]
	v_mul_f32_e32 v152, v136, v136
	v_pk_add_f32 v[116:117], v[116:117], v[118:119]
	v_pk_fma_f32 v[156:157], v[136:137], v[136:137], v[152:153] op_sel_hi:[1,1,0]
	v_pk_add_f32 v[116:117], v[116:117], v[116:117] op_sel_hi:[0,1]
	v_mul_f32_e32 v154, v138, v138
	v_mul_f32_e32 v156, v139, v139
	v_mul_f32_e32 v152, v140, v140
	v_mov_b32_e32 v159, v117
	v_pk_add_f32 v[118:119], v[154:155], v[156:157]
	v_pk_add_f32 v[116:117], v[152:153], v[158:159]
	v_pk_add_f32 v[160:161], v[160:161], v[160:161] op_sel_hi:[0,1]
	v_pk_add_f32 v[116:117], v[118:119], v[116:117]
	v_mul_f32_e32 v164, v150, v150
	v_pk_add_f32 v[116:117], v[116:117], v[116:117] op_sel_hi:[0,1]
	v_mul_f32_e32 v166, v151, v151
	v_mul_f32_e32 v160, v148, v148
	v_mul_f32_e32 v184, v149, v149
	v_mov_b32_e32 v185, v117
	v_pk_add_f32 v[118:119], v[164:165], v[166:167]
	v_pk_add_f32 v[116:117], v[160:161], v[184:185]
	s_nop 0
	v_pk_add_f32 v[116:117], v[118:119], v[116:117]
	s_nop 0
	v_add_f32_e32 v69, v116, v117
	ds_bpermute_b32 v116, v73, v69
	s_waitcnt lgkmcnt(0)
; __device__ __forceinline__ unsigned cvt_pk_bf16(float lo, float hi) { unsigned r; asm volatile("v_cvt_pk_bf16_f32 %0, %1, %2" : "=v"(r) : "v"(lo), "v"(hi)); return r; }
; template <int MODE, bool SRC32>
; __device__ __forceinline__ void phase_mod(const float* x32, _Float16* xh, float* out32, bf16* h, const float* gprev, const float* gain, const float* shiftv, const float* scalev, int wave, int lane) {
;     ...
;             s2 = wave_sum(s2);
;             rstd = 1.0f / sqrtf(s2 * (1.0f / D) + EPS);
;         }
; #pragma unroll
;         for (int j = 0; j < 4; ++j) { const f32x4 o0 = v[2 * j] * rstd * A[2 * j] + Sh[2 * j], o1 = v[2 * j + 1] * rstd * A[2 * j + 1] + Sh[2 * j + 1];
;             u32x4 w; w.x = cvt_pk_bf16(o0[0], o0[1]); w.y = cvt_pk_bf16(o0[2], o0[3]); w.z = cvt_pk_bf16(o1[0], o1[1]); w.w = cvt_pk_bf16(o1[2], o1[3]);
;             *(u32x4*)(h + ro + 512 * j) = w; }
	v_add_f32_e32 v69, v69, v116
	ds_bpermute_b32 v116, v75, v69
	s_waitcnt lgkmcnt(0)
	v_add_f32_e32 v69, v69, v116
	ds_bpermute_b32 v116, v112, v69
	s_waitcnt lgkmcnt(0)
	v_add_f32_e32 v69, v69, v116
	ds_bpermute_b32 v116, v113, v69
	s_waitcnt lgkmcnt(0)
	v_add_f32_e32 v69, v69, v116
	ds_bpermute_b32 v116, v114, v69
	s_waitcnt lgkmcnt(0)
	v_add_f32_e32 v69, v69, v116
	ds_bpermute_b32 v116, v115, v69
	s_waitcnt lgkmcnt(0)
	v_add_f32_e32 v69, v69, v116
	v_fmamk_f32 v69, v69, 0x3a000000, v223
	v_cmp_gt_f32_e32 vcc, s62, v69
	v_mul_f32_e32 v116, 0x4f800000, v69
	s_nop 0
	v_cndmask_b32_e32 v69, v69, v116, vcc
	v_sqrt_f32_e32 v116, v69
	s_nop 0
	v_add_u32_e32 v117, -1, v116
	v_fma_f32 v118, -v117, v116, v69
	v_cmp_ge_f32_e64 s[36:37], 0, v118
	v_add_u32_e32 v118, 1, v116
	s_nop 0
	v_cndmask_b32_e64 v117, v116, v117, s[36:37]
	v_fma_f32 v116, -v118, v116, v69
	v_cmp_lt_f32_e64 s[36:37], 0, v116
	s_nop 1
	v_cndmask_b32_e64 v116, v117, v118, s[36:37]
	v_mul_f32_e32 v117, 0x37800000, v116
	v_cndmask_b32_e32 v116, v116, v117, vcc
	v_cmp_class_f32_e32 vcc, v69, v224
	s_nop 1
	v_cndmask_b32_e32 v69, v116, v69, vcc
	v_div_scale_f32 v116, s[0:1], v69, v69, 1.0
	v_rcp_f32_e32 v117, v116
	s_nop 0
	v_fma_f32 v118, -v116, v117, 1.0
	v_fmac_f32_e32 v117, v118, v117
	v_div_scale_f32 v118, vcc, 1.0, v69, 1.0
	v_mul_f32_e32 v119, v118, v117
	v_fma_f32 v120, -v116, v119, v118
	v_fmac_f32_e32 v119, v120, v117
	v_fma_f32 v116, -v116, v119, v118
	v_div_fmas_f32 v116, v116, v117, v119
	v_div_fixup_f32 v120, v116, v69, 1.0
	v_pk_mul_f32 v[116:117], v[122:123], v[120:121] op_sel_hi:[1,0]
	v_pk_mul_f32 v[118:119], v[124:125], v[120:121] op_sel_hi:[1,0]
	v_pk_fma_f32 v[116:117], v[66:67], v[116:117], v[0:1]
	v_pk_fma_f32 v[118:119], v[64:65], v[118:119], v[2:3]
	v_pk_mul_f32 v[122:123], v[126:127], v[120:121] op_sel_hi:[1,0]
	v_pk_mul_f32 v[124:125], v[128:129], v[120:121] op_sel_hi:[1,0]
	v_add_co_u32_e32 v110, vcc, s26, v110
	v_pk_fma_f32 v[124:125], v[80:81], v[124:125], v[14:15]
	v_pk_fma_f32 v[122:123], v[82:83], v[122:123], v[12:13]
	v_cvt_pk_bf16_f32 v116, v116, v117
	v_cvt_pk_bf16_f32 v117, v118, v119
	v_addc_co_u32_e32 v111, vcc, 0, v111, vcc
	v_cvt_pk_bf16_f32 v118, v122, v123
	v_cvt_pk_bf16_f32 v119, v124, v125
	global_store_dwordx4 v[110:111], v[116:119], off
	v_pk_mul_f32 v[122:123], v[134:135], v[120:121] op_sel_hi:[1,0]
	v_pk_mul_f32 v[124:125], v[136:137], v[120:121] op_sel_hi:[1,0]
	v_pk_mul_f32 v[116:117], v[130:131], v[120:121] op_sel_hi:[1,0]
	v_pk_mul_f32 v[118:119], v[132:133], v[120:121] op_sel_hi:[1,0]
	v_pk_fma_f32 v[116:117], v[86:87], v[116:117], v[20:21]
	v_pk_fma_f32 v[118:119], v[84:85], v[118:119], v[22:23]
	v_pk_fma_f32 v[124:125], v[88:89], v[124:125], v[18:19]
	v_pk_fma_f32 v[122:123], v[90:91], v[122:123], v[16:17]
	v_cvt_pk_bf16_f32 v116, v116, v117
	v_cvt_pk_bf16_f32 v117, v118, v119
	s_nop 0
	v_cvt_pk_bf16_f32 v118, v122, v123
	v_cvt_pk_bf16_f32 v119, v124, v125
	global_store_dwordx4 v[110:111], v[116:119], off offset:1024
	v_pk_mul_f32 v[122:123], v[142:143], v[120:121] op_sel_hi:[1,0]
	v_pk_mul_f32 v[124:125], v[144:145], v[120:121] op_sel_hi:[1,0]
	v_pk_mul_f32 v[116:117], v[138:139], v[120:121] op_sel_hi:[1,0]
	v_pk_mul_f32 v[118:119], v[140:141], v[120:121] op_sel_hi:[1,0]
	v_pk_fma_f32 v[116:117], v[94:95], v[116:117], v[36:37]
	v_pk_fma_f32 v[118:119], v[92:93], v[118:119], v[38:39]
	v_pk_fma_f32 v[124:125], v[96:97], v[124:125], v[34:35]
	v_pk_fma_f32 v[122:123], v[98:99], v[122:123], v[32:33]
	v_cvt_pk_bf16_f32 v116, v116, v117
	v_cvt_pk_bf16_f32 v117, v118, v119
	s_nop 0
	v_cvt_pk_bf16_f32 v118, v122, v123
	v_cvt_pk_bf16_f32 v119, v124, v125
	global_store_dwordx4 v[110:111], v[116:119], off offset:2048
	v_pk_mul_f32 v[122:123], v[150:151], v[120:121] op_sel_hi:[1,0]
	s_nop 0
	v_pk_mul_f32 v[116:117], v[146:147], v[120:121] op_sel_hi:[1,0]
	v_pk_mul_f32 v[118:119], v[162:163], v[120:121] op_sel_hi:[1,0]
	v_pk_fma_f32 v[116:117], v[102:103], v[116:117], v[52:53]
	v_pk_fma_f32 v[118:119], v[100:101], v[118:119], v[54:55]
	v_pk_mul_f32 v[120:121], v[148:149], v[120:121] op_sel_hi:[1,0]
	v_pk_fma_f32 v[122:123], v[106:107], v[122:123], v[48:49]
	v_pk_fma_f32 v[120:121], v[104:105], v[120:121], v[50:51]
	v_cvt_pk_bf16_f32 v116, v116, v117
	v_cvt_pk_bf16_f32 v117, v118, v119
	v_cvt_pk_bf16_f32 v118, v122, v123
	s_nop 0
	v_cvt_pk_bf16_f32 v119, v120, v121
	global_store_dwordx4 v[110:111], v[116:119], off offset:3072
	s_cbranch_scc1 .LBB0_101
	s_mov_b64 s[0:1], 0
